# phase_combine: next trip's rows and LSE entries touched one trip ahead (cache warm-up loads)
# baseline (speedup 1.0000x reference)
; __device__ __forceinline__ int get_tid() { int t = threadIdx.x; asm volatile("" : "+v"(t)); return t; }
; __device__ void phase_combine(const Params& P) {
;     ...
;     for (int idx0 = blockIdx.x * NTHR + get_tid(); idx0 < TH * 64; idx0 += 2 * stride) {
;         float lw[2][3]; u32x4 va[2], vb[2], vc[2]; bf16_t* pp[2]; bool ok[2];
; #pragma unroll
;         for (int k = 0; k < 2; ++k) { const int idx = idx0 + k * stride; ok[k] = idx < TH * 64; const int id2 = ok[k] ? idx : idx0;
;             const int tok = id2 >> 6, c8 = id2 & 63, hh = c8 >> 4, d0 = (c8 & 15) * 8;
;             lw[k][0] = LSE[tok * 12 + hh]; lw[k][1] = LSE[tok * 12 + 4 + hh]; lw[k][2] = LSE[tok * 12 + 8 + hh];
;             pp[k] = Z + (size_t)tok * ZC + ZDQ + hh * 128 + d0;
;             va[k] = *(const u32x4*)pp[k]; vb[k] = *(const u32x4*)(pp[k] + 512); vc[k] = *(const u32x4*)(pp[k] + 1024); }
.LBB0_449:
	v_add_u32_e32 v34, s82, v14
	v_add_u32_e32 v64, s82, v34
	s_mov_b32 s2, 0x100000
	v_cmp_gt_i32_e64 s[100:101], s2, v64
	s_nop 1
	v_cndmask_b32_e64 v64, v14, v64, s[100:101]
	v_add_u32_e32 v84, s82, v64
	s_mov_b32 s2, 0x100000
	v_cmp_gt_i32_e64 s[100:101], s2, v84
	v_readlane_b32 s6, v251, 33
	v_readlane_b32 s7, v251, 34
	v_cndmask_b32_e64 v56, v64, v84, s[100:101]
	v_ashrrev_i32_e32 v57, 6, v56
	v_bfe_u32 v58, v56, 4, 2
	v_mul_lo_u32 v52, v57, 12
	v_or_b32_e32 v52, v52, v58
	v_ashrrev_i32_e32 v53, 31, v52
	v_lshl_add_u64 v[54:55], v[52:53], 2, s[6:7]
	global_load_dword v95, v[54:55], off
	v_add_u32_e32 v54, 4, v52
	v_add_u32_e32 v52, 8, v52
	v_ashrrev_i32_e32 v55, 31, v54
	v_ashrrev_i32_e32 v53, 31, v52
	v_lshl_add_u64 v[54:55], v[54:55], 2, s[6:7]
	v_lshl_add_u64 v[52:53], v[52:53], 2, s[6:7]
	v_mov_b64_e32 v[66:67], s[74:75]
	global_load_dword v95, v[54:55], off
	global_load_dword v95, v[52:53], off
	v_mad_i64_i32 v[52:53], s[4:5], v57, s25, v[66:67]
	v_lshlrev_b32_e32 v194, 8, v58
	v_lshlrev_b32_e32 v54, 4, v56
	v_ashrrev_i32_e32 v70, 6, v64
	v_lshl_add_u64 v[52:53], v[52:53], 0, v[194:195]
	v_and_b32_e32 v194, 0xf0, v54
	v_mul_lo_u32 v65, v70, 12
	v_bfe_u32 v71, v64, 4, 2
	v_lshl_add_u64 v[52:53], v[52:53], 0, v[194:195]
	s_mov_b64 s[8:9], 0x7c59800
	s_mov_b32 s2, 0x7c59000
	v_or_b32_e32 v64, v65, v71
	v_lshl_add_u64 v[76:77], v[52:53], 0, s[8:9]
	v_add_co_u32_e32 v52, vcc, s2, v52
	v_ashrrev_i32_e32 v65, 31, v64
	s_nop 0
	v_addc_co_u32_e32 v53, vcc, 0, v53, vcc
	v_lshl_add_u64 v[68:69], v[64:65], 2, s[6:7]
	global_load_dword v95, v[52:53], off offset:2048
	s_nop 0
	global_load_dword v95, v[76:77], off offset:1024
	global_load_dword v95, v[76:77], off offset:2048
	global_load_dword v95, v[68:69], off
	v_add_u32_e32 v68, 4, v64
	v_add_u32_e32 v64, 8, v64
	v_ashrrev_i32_e32 v69, 31, v68
	v_ashrrev_i32_e32 v65, 31, v64
	v_lshl_add_u64 v[68:69], v[68:69], 2, s[6:7]
	v_lshl_add_u64 v[64:65], v[64:65], 2, s[6:7]
	global_load_dword v95, v[68:69], off
	v_lshlrev_b32_e32 v194, 8, v71
	global_load_dword v95, v[64:65], off
	v_mad_i64_i32 v[64:65], s[4:5], v70, s25, v[66:67]
	v_and_b32_e32 v66, 0x78, v33
	v_lshl_add_u64 v[64:65], v[64:65], 0, v[194:195]
	v_lshlrev_b32_e32 v194, 1, v66
	v_lshl_add_u64 v[64:65], v[64:65], 0, v[194:195]
	v_add_co_u32_e32 v78, vcc, s2, v64
	v_lshl_add_u64 v[72:73], v[64:65], 0, s[8:9]
	s_nop 0
	v_addc_co_u32_e32 v79, vcc, 0, v65, vcc
	global_load_dword v95, v[78:79], off offset:2048
	global_load_dword v95, v[72:73], off offset:1024
	global_load_dword v95, v[72:73], off offset:2048
	s_mov_b32 s2, 0x100000
	v_cmp_gt_i32_e64 s[38:39], s2, v34
	v_readlane_b32 s6, v251, 33
	v_readlane_b32 s7, v251, 34
	v_cndmask_b32_e64 v6, v14, v34, s[38:39]
	v_ashrrev_i32_e32 v7, 6, v6
	v_bfe_u32 v8, v6, 4, 2
	v_mul_lo_u32 v2, v7, 12
	v_or_b32_e32 v2, v2, v8
	v_ashrrev_i32_e32 v3, 31, v2
	v_lshl_add_u64 v[4:5], v[2:3], 2, s[6:7]
	global_load_dword v36, v[4:5], off
	v_add_u32_e32 v4, 4, v2
	v_add_u32_e32 v2, 8, v2
	v_ashrrev_i32_e32 v5, 31, v4
	v_ashrrev_i32_e32 v3, 31, v2
	v_lshl_add_u64 v[4:5], v[4:5], 2, s[6:7]
	v_lshl_add_u64 v[2:3], v[2:3], 2, s[6:7]
	v_mov_b64_e32 v[16:17], s[74:75]
	global_load_dword v35, v[4:5], off
	global_load_dword v37, v[2:3], off
	v_mad_i64_i32 v[2:3], s[4:5], v7, s25, v[16:17]
	v_lshlrev_b32_e32 v194, 8, v8
	v_lshlrev_b32_e32 v4, 4, v6
	v_ashrrev_i32_e32 v20, 6, v14
	v_lshl_add_u64 v[2:3], v[2:3], 0, v[194:195]
	v_and_b32_e32 v194, 0xf0, v4
	v_mul_lo_u32 v15, v20, 12
	v_bfe_u32 v21, v14, 4, 2
	v_lshl_add_u64 v[2:3], v[2:3], 0, v[194:195]
	s_mov_b64 s[8:9], 0x7c59800
	s_mov_b32 s2, 0x7c59000
	v_or_b32_e32 v14, v15, v21
	v_lshl_add_u64 v[26:27], v[2:3], 0, s[8:9]
	v_add_co_u32_e32 v2, vcc, s2, v2
	v_ashrrev_i32_e32 v15, 31, v14
	s_nop 0
	v_addc_co_u32_e32 v3, vcc, 0, v3, vcc
	v_lshl_add_u64 v[18:19], v[14:15], 2, s[6:7]
	global_load_dwordx4 v[2:5], v[2:3], off offset:2048
	s_nop 0
	global_load_dwordx4 v[10:13], v[26:27], off offset:1024
	global_load_dwordx4 v[6:9], v[26:27], off offset:2048
	global_load_dword v42, v[18:19], off
	v_add_u32_e32 v18, 4, v14
	v_add_u32_e32 v14, 8, v14
	v_ashrrev_i32_e32 v19, 31, v18
	v_ashrrev_i32_e32 v15, 31, v14
	v_lshl_add_u64 v[18:19], v[18:19], 2, s[6:7]
	v_lshl_add_u64 v[14:15], v[14:15], 2, s[6:7]
	global_load_dword v43, v[18:19], off
	v_lshlrev_b32_e32 v194, 8, v21
	global_load_dword v44, v[14:15], off
	v_mad_i64_i32 v[14:15], s[4:5], v20, s25, v[16:17]
	v_and_b32_e32 v16, 0x78, v33
	v_lshl_add_u64 v[14:15], v[14:15], 0, v[194:195]
	v_lshlrev_b32_e32 v194, 1, v16
	v_lshl_add_u64 v[14:15], v[14:15], 0, v[194:195]
	v_add_co_u32_e32 v28, vcc, s2, v14
	v_lshl_add_u64 v[22:23], v[14:15], 0, s[8:9]
	s_nop 0
	v_addc_co_u32_e32 v29, vcc, 0, v15, vcc
	global_load_dwordx4 v[14:17], v[28:29], off offset:2048
	global_load_dwordx4 v[18:21], v[22:23], off offset:1024
	global_load_dwordx4 v[22:25], v[22:23], off offset:2048
	s_waitcnt vmcnt(3)
; __device__ __forceinline__ void unpack8(const u32x4 w, float (&f)[8]) { f[0] = bflo(w.x); f[1] = bfhi(w.x); f[2] = bflo(w.y); f[3] = bfhi(w.y); f[4] = bflo(w.z); f[5] = bfhi(w.z); f[6] = bflo(w.w); f[7] = bfhi(w.w); }
; __device__ __forceinline__ u32x4 pack8(const float (&f)[8]) { u32x4 w; w.x = cvt_pk_bf16(f[0], f[1]); w.y = cvt_pk_bf16(f[2], f[3]); w.z = cvt_pk_bf16(f[4], f[5]); w.w = cvt_pk_bf16(f[6], f[7]); return w; }
; __device__ void phase_combine(const Params& P) {
;     ...
;         for (int k = 0; k < 2; ++k) {
;             const float mx = fmaxf(lw[k][0], fmaxf(lw[k][1], lw[k][2]));
;             float w0 = __expf(lw[k][0] - mx), w1 = __expf(lw[k][1] - mx), w2 = __expf(lw[k][2] - mx);
;             const float inv = 1.0f / (w0 + w1 + w2); w0 *= inv; w1 *= inv; w2 *= inv;
;             float a[8], b[8], c[8], o[8];
;             unpack8(va[k], a); unpack8(vb[k], b); unpack8(vc[k], c);
; #pragma unroll
;             for (int j = 0; j < 8; ++j) o[j] = w0 * a[j] + w1 * b[j] + w2 * c[j];
;             if (ok[k]) *(u32x4*)pp[k] = pack8(o);
;         }
	v_max3_f32 v45, v42, v43, v44
	v_sub_f32_e32 v44, v44, v45
	v_mul_f32_e32 v44, 0x3fb8aa3b, v44
	v_sub_f32_e32 v46, v42, v45
	v_exp_f32_e32 v30, v44
	v_sub_f32_e32 v44, v43, v45
	v_mul_f32_e32 v46, 0x3fb8aa3b, v46
	v_mul_f32_e32 v44, 0x3fb8aa3b, v44
	v_exp_f32_e32 v31, v46
	v_exp_f32_e32 v43, v44
	s_nop 0
	v_add_f32_e32 v44, v31, v43
	v_add_f32_e32 v44, v30, v44
	v_div_scale_f32 v45, s[4:5], v44, v44, 1.0
	v_rcp_f32_e32 v46, v45
	s_nop 0
	v_fma_f32 v42, -v45, v46, 1.0
	v_fmac_f32_e32 v46, v42, v46
	v_div_scale_f32 v42, vcc, 1.0, v44, 1.0
	v_mul_f32_e32 v47, v42, v46
	v_fma_f32 v48, -v45, v47, v42
	v_fmac_f32_e32 v47, v48, v46
	v_fma_f32 v45, -v45, v47, v42
	v_div_fmas_f32 v45, v45, v46, v47
	v_div_fixup_f32 v32, v45, v44, 1.0
	v_mul_f32_e32 v40, v43, v32
	v_pk_mul_f32 v[30:31], v[30:31], v[32:33] op_sel_hi:[1,0]
	s_waitcnt vmcnt(2)
	v_and_b32_e32 v39, 0xffff0000, v17
	s_waitcnt vmcnt(1)
	v_and_b32_e32 v41, 0xffff0000, v21
	v_lshlrev_b32_e32 v21, 16, v21
	s_waitcnt vmcnt(0)
	v_and_b32_e32 v38, 0xffff0000, v25
	v_pk_mul_f32 v[38:39], v[30:31], v[38:39]
	s_nop 0
	v_fma_f32 v32, v40, v41, v39
	v_add_f32_e32 v32, v38, v32
	v_lshlrev_b32_e32 v39, 16, v17
	v_lshlrev_b32_e32 v38, 16, v25
	v_pk_mul_f32 v[38:39], v[30:31], v[38:39]
	s_nop 0
	v_fma_f32 v17, v40, v21, v39
	v_add_f32_e32 v21, v38, v17
	v_and_b32_e32 v39, 0xffff0000, v16
	v_and_b32_e32 v38, 0xffff0000, v24
	v_and_b32_e32 v17, 0xffff0000, v20
	v_pk_mul_f32 v[38:39], v[30:31], v[38:39]
	v_lshlrev_b32_e32 v20, 16, v20
	v_fma_f32 v17, v40, v17, v39
	v_add_f32_e32 v25, v38, v17
	v_lshlrev_b32_e32 v17, 16, v16
	v_lshlrev_b32_e32 v16, 16, v24
	v_pk_mul_f32 v[16:17], v[30:31], v[16:17]
	v_and_b32_e32 v24, 0xffff0000, v19
	v_fma_f32 v17, v40, v20, v17
	v_add_f32_e32 v20, v16, v17
	v_and_b32_e32 v17, 0xffff0000, v15
	v_and_b32_e32 v16, 0xffff0000, v23
	v_pk_mul_f32 v[16:17], v[30:31], v[16:17]
	v_lshlrev_b32_e32 v19, 16, v19
	v_fma_f32 v17, v40, v24, v17
	v_add_f32_e32 v24, v16, v17
	v_lshlrev_b32_e32 v17, 16, v15
	v_lshlrev_b32_e32 v16, 16, v23
	v_pk_mul_f32 v[16:17], v[30:31], v[16:17]
	s_nop 0
	v_fma_f32 v15, v40, v19, v17
	v_add_f32_e32 v19, v16, v15
	v_and_b32_e32 v17, 0xffff0000, v14
	v_and_b32_e32 v16, 0xffff0000, v22
	v_and_b32_e32 v15, 0xffff0000, v18
	v_pk_mul_f32 v[16:17], v[30:31], v[16:17]
	s_nop 0
	v_fma_f32 v15, v40, v15, v17
	v_add_f32_e32 v16, v16, v15
	v_lshlrev_b32_e32 v15, 16, v14
	v_lshlrev_b32_e32 v14, 16, v22
	v_lshlrev_b32_e32 v17, 16, v18
	v_pk_mul_f32 v[14:15], v[30:31], v[14:15]
	s_nop 0
	v_fma_f32 v15, v40, v17, v15
	v_add_f32_e32 v14, v14, v15
	v_cvt_pk_bf16_f32 v14, v14, v16
	v_cvt_pk_bf16_f32 v15, v19, v24
	v_cvt_pk_bf16_f32 v16, v20, v25
	v_cvt_pk_bf16_f32 v17, v21, v32
	global_store_dwordx4 v[28:29], v[14:17], off offset:2048
	s_and_saveexec_b64 s[40:41], s[38:39]
	s_cbranch_execz .LBB0_448
	v_max3_f32 v14, v36, v35, v37
	v_sub_f32_e32 v15, v36, v14
	v_sub_f32_e32 v16, v37, v14
	v_sub_f32_e32 v14, v35, v14
	v_mul_f32_e32 v15, 0x3fb8aa3b, v15
	v_mul_f32_e32 v14, 0x3fb8aa3b, v14
	v_exp_f32_e32 v15, v15
	v_mul_f32_e32 v16, 0x3fb8aa3b, v16
	v_exp_f32_e32 v17, v14
	v_exp_f32_e32 v14, v16
	v_add_f32_e32 v16, v15, v17
	v_add_f32_e32 v16, v14, v16
	v_div_scale_f32 v18, s[4:5], v16, v16, 1.0
	v_rcp_f32_e32 v19, v18
	s_nop 0
	v_fma_f32 v20, -v18, v19, 1.0
	v_fmac_f32_e32 v19, v20, v19
	v_div_scale_f32 v20, vcc, 1.0, v16, 1.0
	v_mul_f32_e32 v21, v20, v19
	v_fma_f32 v22, -v18, v21, v20
	v_fmac_f32_e32 v21, v22, v19
	v_fma_f32 v18, -v18, v21, v20
	v_div_fmas_f32 v18, v18, v19, v21
	v_div_fixup_f32 v16, v18, v16, 1.0
	v_mul_f32_e32 v18, v17, v16
	v_pk_mul_f32 v[14:15], v[14:15], v[16:17] op_sel_hi:[1,0]
	v_and_b32_e32 v17, 0xffff0000, v5
	v_and_b32_e32 v16, 0xffff0000, v9
	v_and_b32_e32 v19, 0xffff0000, v13
	v_pk_mul_f32 v[16:17], v[14:15], v[16:17]
	v_lshlrev_b32_e32 v13, 16, v13
	v_fma_f32 v17, v18, v19, v17
	v_add_f32_e32 v19, v16, v17
	v_lshlrev_b32_e32 v17, 16, v5
	v_lshlrev_b32_e32 v16, 16, v9
	v_pk_mul_f32 v[16:17], v[14:15], v[16:17]
	s_nop 0
	v_fma_f32 v5, v18, v13, v17
	v_add_f32_e32 v9, v16, v5
	v_and_b32_e32 v17, 0xffff0000, v4
	v_and_b32_e32 v16, 0xffff0000, v8
	v_and_b32_e32 v5, 0xffff0000, v12
	v_pk_mul_f32 v[16:17], v[14:15], v[16:17]
	v_lshlrev_b32_e32 v12, 16, v12
	v_fma_f32 v5, v18, v5, v17
	v_add_f32_e32 v13, v16, v5
	v_lshlrev_b32_e32 v5, 16, v4
	v_lshlrev_b32_e32 v4, 16, v8
	v_pk_mul_f32 v[4:5], v[14:15], v[4:5]
	s_nop 0
	v_fma_f32 v5, v18, v12, v5
	v_add_f32_e32 v8, v4, v5
	v_and_b32_e32 v5, 0xffff0000, v3
	v_and_b32_e32 v4, 0xffff0000, v7
	v_and_b32_e32 v12, 0xffff0000, v11
	v_pk_mul_f32 v[4:5], v[14:15], v[4:5]
	v_lshlrev_b32_e32 v11, 16, v11
	v_fma_f32 v5, v18, v12, v5
	v_add_f32_e32 v12, v4, v5
	v_lshlrev_b32_e32 v5, 16, v3
	v_lshlrev_b32_e32 v4, 16, v7
	v_pk_mul_f32 v[4:5], v[14:15], v[4:5]
	s_nop 0
	v_fma_f32 v3, v18, v11, v5
	v_add_f32_e32 v7, v4, v3
	v_and_b32_e32 v5, 0xffff0000, v2
	v_and_b32_e32 v4, 0xffff0000, v6
	v_and_b32_e32 v3, 0xffff0000, v10
	v_pk_mul_f32 v[4:5], v[14:15], v[4:5]
	s_nop 0
	v_fma_f32 v3, v18, v3, v5
	v_add_f32_e32 v4, v4, v3
	v_lshlrev_b32_e32 v3, 16, v2
	v_lshlrev_b32_e32 v2, 16, v6
	v_lshlrev_b32_e32 v5, 16, v10
	v_pk_mul_f32 v[2:3], v[14:15], v[2:3]
	s_nop 0
	v_fma_f32 v3, v18, v5, v3
	v_add_f32_e32 v2, v2, v3
	v_cvt_pk_bf16_f32 v2, v2, v4
	v_cvt_pk_bf16_f32 v3, v7, v12
	v_cvt_pk_bf16_f32 v4, v8, v13
	v_cvt_pk_bf16_f32 v5, v9, v19
	global_store_dwordx4 v[26:27], v[2:5], off
	s_branch .LBB0_448
